# v83 + G9 epilogue: 107 canonicalising v_max x,x removed ahead of v_max 0,x (squared ReLU), with wide-store data WAR pads
# baseline (speedup 1.0000x reference)
.LBB0_1029:
	v_lshl_add_u32 v146, s41, 8, v129
	v_max_f32_e32 v120, 0, v120
	v_lshl_or_b32 v140, s40, 8, v143
	v_ashrrev_i32_e32 v147, 31, v146
	v_mul_f32_e32 v145, v120, v120
	v_max_f32_e32 v121, 0, v121
	v_max_f32_e32 v122, 0, v122
	v_ashrrev_i32_e32 v141, 31, v140
	v_lshlrev_b64 v[148:149], 14, v[146:147]
	v_max_f32_e32 v120, 0, v125
	v_mul_f32_e32 v125, v121, v121
	v_max_f32_e32 v121, v126, v126
	v_mul_f32_e32 v126, v122, v122
	v_lshl_add_u64 v[148:149], s[4:5], 0, v[148:149]
	v_lshlrev_b64 v[150:151], 1, v[140:141]
	v_max_f32_e32 v124, 0, v124
	v_mul_f32_e32 v120, v120, v120
	v_max_f32_e32 v121, 0, v121
	v_max_f32_e32 v122, 0, v127
	v_max_f32_e32 v123, 0, v123
	v_lshl_add_u64 v[140:141], v[148:149], 0, v[150:151]
	v_mul_f32_e32 v124, v124, v124
	v_mul_f32_e32 v121, v121, v121
	v_mul_f32_e32 v122, v122, v122
	v_mul_f32_e32 v123, v123, v123
	v_cvt_pk_bf16_f32 v120, v124, v120
	v_max_f32_e32 v112, 0, v112
	v_cvt_pk_bf16_f32 v121, v121, v122
	v_cvt_pk_bf16_f32 v122, v145, v125
	v_cvt_pk_bf16_f32 v123, v126, v123
	global_store_dwordx4 v[140:141], v[120:123], off
	v_max_f32_e32 v113, 0, v113
	v_max_f32_e32 v114, 0, v114
	v_mul_f32_e32 v120, v112, v112
	v_max_f32_e32 v112, 0, v117
	v_mul_f32_e32 v117, v113, v113
	v_max_f32_e32 v113, v118, v118
	v_mul_f32_e32 v118, v114, v114
	v_max_f32_e32 v116, 0, v116
	v_mul_f32_e32 v112, v112, v112
	v_max_f32_e32 v113, 0, v113
	v_max_f32_e32 v114, 0, v119
	v_max_f32_e32 v115, 0, v115
	v_mul_f32_e32 v116, v116, v116
	v_mul_f32_e32 v113, v113, v113
	v_mul_f32_e32 v114, v114, v114
	v_mul_f32_e32 v115, v115, v115
	v_cvt_pk_bf16_f32 v112, v116, v112
	v_cvt_pk_bf16_f32 v113, v113, v114
	v_cvt_pk_bf16_f32 v114, v120, v117
	v_cvt_pk_bf16_f32 v115, v118, v115
	global_store_dwordx4 v[140:141], v[112:115], off offset:256
	s_nop 1
	v_max_f32_e32 v104, 0, v104
	v_or_b32_e32 v112, 16, v146
	v_ashrrev_i32_e32 v113, 31, v112
	v_mul_f32_e32 v114, v104, v104
	v_max_f32_e32 v105, 0, v105
	v_max_f32_e32 v106, 0, v106
	v_lshlrev_b64 v[112:113], 14, v[112:113]
	v_max_f32_e32 v104, 0, v109
	v_mul_f32_e32 v109, v105, v105
	v_max_f32_e32 v105, v110, v110
	v_mul_f32_e32 v110, v106, v106
	v_lshl_add_u64 v[112:113], s[4:5], 0, v[112:113]
	v_max_f32_e32 v108, 0, v108
	v_mul_f32_e32 v104, v104, v104
	v_max_f32_e32 v105, 0, v105
	v_max_f32_e32 v106, 0, v111
	v_max_f32_e32 v107, 0, v107
	v_lshl_add_u64 v[112:113], v[112:113], 0, v[150:151]
	v_mul_f32_e32 v108, v108, v108
	v_mul_f32_e32 v105, v105, v105
	v_mul_f32_e32 v106, v106, v106
	v_mul_f32_e32 v107, v107, v107
	v_cvt_pk_bf16_f32 v104, v108, v104
	v_max_f32_e32 v96, 0, v96
	v_cvt_pk_bf16_f32 v105, v105, v106
	v_cvt_pk_bf16_f32 v106, v114, v109
	v_cvt_pk_bf16_f32 v107, v110, v107
	global_store_dwordx4 v[112:113], v[104:107], off
	v_max_f32_e32 v97, 0, v97
	v_max_f32_e32 v98, 0, v98
	v_mul_f32_e32 v104, v96, v96
	v_max_f32_e32 v96, 0, v101
	v_mul_f32_e32 v101, v97, v97
	v_max_f32_e32 v97, v102, v102
	v_mul_f32_e32 v102, v98, v98
	v_max_f32_e32 v100, 0, v100
	v_mul_f32_e32 v96, v96, v96
	v_max_f32_e32 v97, 0, v97
	v_max_f32_e32 v98, 0, v103
	v_max_f32_e32 v99, 0, v99
	v_mul_f32_e32 v100, v100, v100
	v_mul_f32_e32 v97, v97, v97
	v_mul_f32_e32 v98, v98, v98
	v_mul_f32_e32 v99, v99, v99
	v_cvt_pk_bf16_f32 v96, v100, v96
	v_cvt_pk_bf16_f32 v97, v97, v98
	v_cvt_pk_bf16_f32 v98, v104, v101
	v_cvt_pk_bf16_f32 v99, v102, v99
	global_store_dwordx4 v[112:113], v[96:99], off offset:256
	s_nop 1
	v_max_f32_e32 v88, 0, v88
	v_or_b32_e32 v96, 32, v146
	v_ashrrev_i32_e32 v97, 31, v96
	v_mul_f32_e32 v98, v88, v88
	v_max_f32_e32 v89, 0, v89
	v_max_f32_e32 v90, 0, v90
	v_lshlrev_b64 v[96:97], 14, v[96:97]
	v_max_f32_e32 v88, 0, v93
	v_mul_f32_e32 v93, v89, v89
	v_max_f32_e32 v89, v94, v94
	v_mul_f32_e32 v94, v90, v90
	v_lshl_add_u64 v[96:97], s[4:5], 0, v[96:97]
	v_max_f32_e32 v92, 0, v92
	v_mul_f32_e32 v88, v88, v88
	v_max_f32_e32 v89, 0, v89
	v_max_f32_e32 v90, 0, v95
	v_max_f32_e32 v91, 0, v91
	v_lshl_add_u64 v[96:97], v[96:97], 0, v[150:151]
	v_mul_f32_e32 v92, v92, v92
	v_mul_f32_e32 v89, v89, v89
	v_mul_f32_e32 v90, v90, v90
	v_mul_f32_e32 v91, v91, v91
	v_cvt_pk_bf16_f32 v88, v92, v88
	v_max_f32_e32 v80, 0, v80
	v_cvt_pk_bf16_f32 v89, v89, v90
	v_cvt_pk_bf16_f32 v90, v98, v93
	v_cvt_pk_bf16_f32 v91, v94, v91
	global_store_dwordx4 v[96:97], v[88:91], off
	v_max_f32_e32 v81, 0, v81
	v_max_f32_e32 v82, 0, v82
	v_mul_f32_e32 v88, v80, v80
	v_max_f32_e32 v80, 0, v85
	v_mul_f32_e32 v85, v81, v81
	v_max_f32_e32 v81, v86, v86
	v_mul_f32_e32 v86, v82, v82
	v_max_f32_e32 v84, 0, v84
	v_mul_f32_e32 v80, v80, v80
	v_max_f32_e32 v81, 0, v81
	v_max_f32_e32 v82, 0, v87
	v_max_f32_e32 v83, 0, v83
	v_mul_f32_e32 v84, v84, v84
	v_mul_f32_e32 v81, v81, v81
	v_mul_f32_e32 v82, v82, v82
	v_mul_f32_e32 v83, v83, v83
	v_cvt_pk_bf16_f32 v80, v84, v80
	v_cvt_pk_bf16_f32 v81, v81, v82
	v_cvt_pk_bf16_f32 v82, v88, v85
	v_cvt_pk_bf16_f32 v83, v86, v83
	global_store_dwordx4 v[96:97], v[80:83], off offset:256
	s_nop 1
	v_max_f32_e32 v72, 0, v72
	v_or_b32_e32 v80, 48, v146
	v_ashrrev_i32_e32 v81, 31, v80
	v_mul_f32_e32 v82, v72, v72
	v_max_f32_e32 v73, 0, v73
	v_max_f32_e32 v74, 0, v74
	v_lshlrev_b64 v[80:81], 14, v[80:81]
	v_max_f32_e32 v72, 0, v77
	v_mul_f32_e32 v77, v73, v73
	v_max_f32_e32 v73, v78, v78
	v_mul_f32_e32 v78, v74, v74
	v_lshl_add_u64 v[80:81], s[4:5], 0, v[80:81]
	v_max_f32_e32 v76, 0, v76
	v_mul_f32_e32 v72, v72, v72
	v_max_f32_e32 v73, 0, v73
	v_max_f32_e32 v74, 0, v79
	v_max_f32_e32 v75, 0, v75
	v_lshl_add_u64 v[80:81], v[80:81], 0, v[150:151]
	v_mul_f32_e32 v76, v76, v76
	v_mul_f32_e32 v73, v73, v73
	v_mul_f32_e32 v74, v74, v74
	v_mul_f32_e32 v75, v75, v75
	v_cvt_pk_bf16_f32 v72, v76, v72
	v_max_f32_e32 v64, 0, v64
	v_max_f32_e32 v65, 0, v65
	v_max_f32_e32 v66, 0, v66
	v_cvt_pk_bf16_f32 v73, v73, v74
	v_cvt_pk_bf16_f32 v74, v82, v77
	v_cvt_pk_bf16_f32 v75, v78, v75
	global_store_dwordx4 v[80:81], v[72:75], off
	s_nop 1
	v_mul_f32_e32 v72, v64, v64
	v_max_f32_e32 v64, v69, v69
	v_mul_f32_e32 v69, v65, v65
	v_max_f32_e32 v65, v70, v70
	v_mul_f32_e32 v70, v66, v66
	v_max_f32_e32 v64, 0, v64
	v_max_f32_e32 v65, 0, v65
	v_max_f32_e32 v66, 0, v71
	v_max_f32_e32 v68, 0, v68
	v_mul_f32_e32 v64, v64, v64
	v_mul_f32_e32 v65, v65, v65
	v_max_f32_e32 v67, 0, v67
	v_mul_f32_e32 v66, v66, v66
	v_mul_f32_e32 v68, v68, v68
	v_mul_f32_e32 v67, v67, v67
	v_cvt_pk_bf16_f32 v64, v68, v64
	v_cvt_pk_bf16_f32 v65, v65, v66
	v_cvt_pk_bf16_f32 v66, v72, v69
	v_max_f32_e32 v56, 0, v56
	v_cvt_pk_bf16_f32 v67, v70, v67
	global_store_dwordx4 v[80:81], v[64:67], off offset:256
	s_nop 1
	v_max_f32_e32 v57, 0, v57
	v_mul_f32_e32 v66, v56, v56
	v_max_f32_e32 v58, 0, v58
	v_max_f32_e32 v60, 0, v60
	v_max_f32_e32 v56, 0, v61
	v_mul_f32_e32 v61, v57, v57
	v_max_f32_e32 v57, v62, v62
	v_mul_f32_e32 v62, v58, v58
	v_mul_f32_e32 v60, v60, v60
	v_mul_f32_e32 v56, v56, v56
	v_max_f32_e32 v57, 0, v57
	v_max_f32_e32 v58, 0, v63
	s_mov_b32 s13, 0x200000
	v_mul_f32_e32 v57, v57, v57
	v_max_f32_e32 v59, 0, v59
	v_mul_f32_e32 v58, v58, v58
	v_cvt_pk_bf16_f32 v56, v60, v56
	v_add_co_u32_e32 v60, vcc, s13, v140
	v_mul_f32_e32 v59, v59, v59
	v_cvt_pk_bf16_f32 v57, v57, v58
	v_cvt_pk_bf16_f32 v58, v66, v61
	v_addc_co_u32_e32 v61, vcc, 0, v141, vcc
	v_max_f32_e32 v48, 0, v48
	v_max_f32_e32 v49, 0, v49
	v_max_f32_e32 v50, 0, v50
	v_cvt_pk_bf16_f32 v59, v62, v59
	global_store_dwordx4 v[60:61], v[56:59], off
	s_nop 1
	v_mul_f32_e32 v56, v48, v48
	v_max_f32_e32 v48, v53, v53
	v_mul_f32_e32 v53, v49, v49
	v_max_f32_e32 v49, v54, v54
	v_mul_f32_e32 v54, v50, v50
	v_max_f32_e32 v48, 0, v48
	v_max_f32_e32 v49, 0, v49
	v_max_f32_e32 v50, 0, v55
	s_mov_b64 s[20:21], 0x200000
	v_max_f32_e32 v52, 0, v52
	v_mul_f32_e32 v48, v48, v48
	v_mul_f32_e32 v49, v49, v49
	v_max_f32_e32 v51, 0, v51
	v_mul_f32_e32 v50, v50, v50
	v_lshl_add_u64 v[64:65], v[140:141], 0, s[20:21]
	v_mul_f32_e32 v52, v52, v52
	v_mul_f32_e32 v51, v51, v51
	v_cvt_pk_bf16_f32 v48, v52, v48
	v_cvt_pk_bf16_f32 v49, v49, v50
	v_cvt_pk_bf16_f32 v50, v56, v53
	v_max_f32_e32 v40, 0, v40
	v_cvt_pk_bf16_f32 v51, v54, v51
	global_store_dwordx4 v[64:65], v[48:51], off offset:256
	s_nop 1
	v_max_f32_e32 v41, 0, v41
	v_mul_f32_e32 v50, v40, v40
	v_max_f32_e32 v42, 0, v42
	v_max_f32_e32 v44, 0, v44
	v_max_f32_e32 v40, 0, v45
	v_mul_f32_e32 v45, v41, v41
	v_max_f32_e32 v41, v46, v46
	v_mul_f32_e32 v46, v42, v42
	v_mul_f32_e32 v44, v44, v44
	v_mul_f32_e32 v40, v40, v40
	v_max_f32_e32 v41, 0, v41
	v_max_f32_e32 v42, 0, v47
	s_mov_b32 s13, 0x240000
	v_mul_f32_e32 v41, v41, v41
	v_max_f32_e32 v43, 0, v43
	v_mul_f32_e32 v42, v42, v42
	v_cvt_pk_bf16_f32 v40, v44, v40
	v_add_co_u32_e32 v44, vcc, s13, v140
	v_mul_f32_e32 v43, v43, v43
	v_cvt_pk_bf16_f32 v41, v41, v42
	v_cvt_pk_bf16_f32 v42, v50, v45
	v_addc_co_u32_e32 v45, vcc, 0, v141, vcc
	v_max_f32_e32 v32, 0, v32
	v_max_f32_e32 v33, 0, v33
	v_max_f32_e32 v34, 0, v34
	v_cvt_pk_bf16_f32 v43, v46, v43
	global_store_dwordx4 v[44:45], v[40:43], off
	s_nop 1
	v_mul_f32_e32 v40, v32, v32
	v_max_f32_e32 v32, v37, v37
	v_mul_f32_e32 v37, v33, v33
	v_max_f32_e32 v33, v38, v38
	v_mul_f32_e32 v38, v34, v34
	v_max_f32_e32 v32, 0, v32
	v_max_f32_e32 v33, 0, v33
	v_max_f32_e32 v34, 0, v39
	s_mov_b64 s[20:21], 0x240000
	v_max_f32_e32 v36, 0, v36
	v_mul_f32_e32 v32, v32, v32
	v_mul_f32_e32 v33, v33, v33
	v_max_f32_e32 v35, 0, v35
	v_mul_f32_e32 v34, v34, v34
	v_lshl_add_u64 v[48:49], v[140:141], 0, s[20:21]
	v_mul_f32_e32 v36, v36, v36
	v_mul_f32_e32 v35, v35, v35
	v_cvt_pk_bf16_f32 v32, v36, v32
	v_cvt_pk_bf16_f32 v33, v33, v34
	v_cvt_pk_bf16_f32 v34, v40, v37
	v_max_f32_e32 v24, 0, v24
	v_cvt_pk_bf16_f32 v35, v38, v35
	global_store_dwordx4 v[48:49], v[32:35], off offset:256
	s_nop 1
	v_max_f32_e32 v25, 0, v25
	v_mul_f32_e32 v34, v24, v24
	v_max_f32_e32 v26, 0, v26
	v_max_f32_e32 v28, 0, v28
	v_max_f32_e32 v24, 0, v29
	v_mul_f32_e32 v29, v25, v25
	v_max_f32_e32 v25, v30, v30
	v_mul_f32_e32 v30, v26, v26
	v_mul_f32_e32 v28, v28, v28
	v_mul_f32_e32 v24, v24, v24
	v_max_f32_e32 v25, 0, v25
	v_max_f32_e32 v26, 0, v31
	s_mov_b32 s13, 0x280000
	v_mul_f32_e32 v25, v25, v25
	v_max_f32_e32 v27, 0, v27
	v_mul_f32_e32 v26, v26, v26
	v_cvt_pk_bf16_f32 v24, v28, v24
	v_add_co_u32_e32 v28, vcc, s13, v140
	v_mul_f32_e32 v27, v27, v27
	v_cvt_pk_bf16_f32 v25, v25, v26
	v_cvt_pk_bf16_f32 v26, v34, v29
	v_addc_co_u32_e32 v29, vcc, 0, v141, vcc
	v_max_f32_e32 v16, 0, v16
	v_max_f32_e32 v17, 0, v17
	v_max_f32_e32 v18, 0, v18
	v_cvt_pk_bf16_f32 v27, v30, v27
	global_store_dwordx4 v[28:29], v[24:27], off
	s_nop 1
	v_mul_f32_e32 v24, v16, v16
	v_max_f32_e32 v16, v21, v21
	v_mul_f32_e32 v21, v17, v17
	v_max_f32_e32 v17, v22, v22
	v_mul_f32_e32 v22, v18, v18
	v_max_f32_e32 v16, 0, v16
	v_max_f32_e32 v17, 0, v17
	v_max_f32_e32 v18, 0, v23
	s_mov_b64 s[20:21], 0x280000
	v_max_f32_e32 v20, 0, v20
	v_mul_f32_e32 v16, v16, v16
	v_mul_f32_e32 v17, v17, v17
	v_max_f32_e32 v19, 0, v19
	v_mul_f32_e32 v18, v18, v18
	v_lshl_add_u64 v[32:33], v[140:141], 0, s[20:21]
	v_mul_f32_e32 v20, v20, v20
	v_mul_f32_e32 v19, v19, v19
	v_cvt_pk_bf16_f32 v16, v20, v16
	v_cvt_pk_bf16_f32 v17, v17, v18
	v_cvt_pk_bf16_f32 v18, v24, v21
	v_max_f32_e32 v8, 0, v8
	v_cvt_pk_bf16_f32 v19, v22, v19
	global_store_dwordx4 v[32:33], v[16:19], off offset:256
	s_nop 1
	v_max_f32_e32 v9, 0, v9
	v_mul_f32_e32 v18, v8, v8
	v_max_f32_e32 v10, 0, v10
	v_max_f32_e32 v12, 0, v12
	v_max_f32_e32 v8, 0, v13
	v_mul_f32_e32 v13, v9, v9
	v_max_f32_e32 v9, v14, v14
	v_mul_f32_e32 v14, v10, v10
	v_mul_f32_e32 v12, v12, v12
	v_mul_f32_e32 v8, v8, v8
	v_max_f32_e32 v9, 0, v9
	v_max_f32_e32 v10, 0, v15
	s_mov_b32 s13, 0x2c0000
	v_mul_f32_e32 v9, v9, v9
	v_max_f32_e32 v11, 0, v11
	v_mul_f32_e32 v10, v10, v10
	v_cvt_pk_bf16_f32 v8, v12, v8
	v_add_co_u32_e32 v12, vcc, s13, v140
	v_mul_f32_e32 v11, v11, v11
	v_cvt_pk_bf16_f32 v9, v9, v10
	v_cvt_pk_bf16_f32 v10, v18, v13
	v_addc_co_u32_e32 v13, vcc, 0, v141, vcc
	v_max_f32_e32 v0, 0, v0
	v_max_f32_e32 v1, 0, v1
	v_max_f32_e32 v2, 0, v2
	v_cvt_pk_bf16_f32 v11, v14, v11
	global_store_dwordx4 v[12:13], v[8:11], off
	s_nop 1
	s_mov_b64 s[20:21], 0x2c0000
	v_mul_f32_e32 v8, v0, v0
	v_max_f32_e32 v0, v5, v5
	v_mul_f32_e32 v5, v1, v1
	v_max_f32_e32 v1, v6, v6
	v_mul_f32_e32 v6, v2, v2
	v_max_f32_e32 v0, 0, v0
	v_max_f32_e32 v1, 0, v1
	v_max_f32_e32 v2, 0, v7
	v_max_f32_e32 v3, 0, v3
	v_lshl_add_u64 v[16:17], v[140:141], 0, s[20:21]
	v_max_f32_e32 v4, 0, v4
	v_mul_f32_e32 v0, v0, v0
	v_mul_f32_e32 v1, v1, v1
	v_mul_f32_e32 v2, v2, v2
	v_mul_f32_e32 v3, v3, v3
	s_andn2_b64 vcc, exec, s[0:1]
	s_mov_b64 s[0:1], -1
	v_mul_f32_e32 v4, v4, v4
	v_cvt_pk_bf16_f32 v0, v4, v0
	v_cvt_pk_bf16_f32 v1, v1, v2
	v_cvt_pk_bf16_f32 v2, v8, v5
	v_cvt_pk_bf16_f32 v3, v6, v3
	global_store_dwordx4 v[16:17], v[0:3], off offset:256
	s_cbranch_vccnz .LBB0_1018
	s_andn2_b64 vcc, exec, s[2:3]
	s_cbranch_vccnz .LBB0_1017
	s_barrier
	s_branch .LBB0_1017
